# diff near-diagonal LUT path: 16 bias reads batched (one wait), causal mask folded into lut[-1] = -inf; on top of sparse far-stage rewrite
# speedup vs baseline: 1.0210x; 1.0026x over previous
; DI int swap23(int k) { return (k & ~12) | ((k & 4) << 1) | ((k & 8) >> 1); }
; DI void build_lut(const Params& p, int bias_head, unsigned char* smem, int tid) {
;   float* lut = (float*)(smem + LUT_OFF);
;   const int d = tid;
;   if (d <= 128) {
;     int bucket;
;     if (d < 16) bucket = d;
;     else {
;       float nf = (float)d;
;       int large = 16 + (int)(logf(nf / 16.f) / 2.0794415416798357f * 16.f);
;       bucket = large < 31 ? large : 31;
;     }
;     lut[d] = p.rel_bias[bucket * 8 + bias_head] * LOG2E;
;   }
; }
; DI void diff_job8(const Params& p, int layer, int b, int head, int qb, unsigned char* smem) {
;   int tid_ = threadIdx.x; asm volatile("" : "+v"(tid_));
;   const int tid = tid_, lane = tid & 63, wave = tid >> 6, h = lane >> 5, lq = lane & 31;
;   const int map = wave >> 2, qg = wave & 3;
;   const int t0 = qb * 128, tw0 = t0 + 32 * qg, tq = tw0 + lq;
;   const float* lut = (const float*)(smem + LUT_OFF);
;   build_lut(p, 4 + head, smem, tid);
;   bf16x8 qf[4];
;   {
;     const u16* qr = p.qdf + (size_t)(b * TP + tq) * 512 + head * 128 + 64 * map + 8 * h;
; #pragma unroll
;     for (int s = 0; s < 4; ++s) qf[s] = *(const bf16x8*)(qr + 16 * s);
;   }
;   f32x16 O[4];
; #pragma unroll
;   for (int i = 0; i < 4; ++i) O[i] = zero16();
;   float m = -1e30f, l = 0.f;
;   const u16* K1 = p.kdf + (size_t)b * TP * 512 + head * 128;
;   const u16* VT = p.vtdf + (size_t)(b * 512 + head * 128) * TP;
;   const int ntile = 2 * (qb + 1);
;   const int krow = tid >> 3, kc = tid & 7, krs = swap23(krow);
;   u32x4 rk1, rk2, rv[2];
;   auto gl = [&](int k0) {
;     const u16* s = K1 + (size_t)(k0 + krow) * 512 + kc * 8;
;     rk1 = *(const u32x4*)s; rk2 = *(const u32x4*)(s + 64);
; #pragma unroll
;     for (int i = 0; i < 2; ++i) rv[i] = *(const u32x4*)(VT + (size_t)(krow + 64 * i) * TP + k0 + kc * 8);
;   };
;   auto sl = [&](unsigned char* d) {
;     *(u32x4*)(d + krs * 144 + kc * 16) = rk1;
;     *(u32x4*)(d + 9216 + krs * 144 + kc * 16) = rk2;
; #pragma unroll
;     for (int i = 0; i < 2; ++i) *(u32x4*)(d + 18432 + (krow + 64 * i) * 144 + kc * 16) = rv[i];
;   };
;   gl(0); sl(smem);
;   if (ntile > 1) gl(64);
;   __syncthreads();
.LBB0_918:
	s_or_b64 exec, exec, s[2:3]
	s_ashr_i32 s2, s10, 31
	s_lshr_b32 s2, s2, 27
	s_add_i32 s2, s10, s2
	s_ashr_i32 s2, s2, 5
	v_lshrrev_b32_e32 v0, 1, v150
	s_load_dwordx16 s[56:71], s[0:1], 0x108
	s_sub_i32 s7, 32, s2
	v_and_b32_e32 v149, 0x60, v0
	s_bfe_u32 s4, s10, 0x30002
	v_and_b32_e32 v148, 31, v150
	v_lshl_or_b32 v152, s7, 7, v149
	v_or_b32_e32 v153, v152, v148
	s_mul_i32 s2, s4, 0x1080
	v_add_u32_e32 v0, s2, v153
	s_lshl_b32 s31, s6, 7
	s_lshl_b32 s10, s6, 8
	s_mul_i32 s2, s4, 0x420000
	v_ashrrev_i32_e32 v131, 8, v150
	v_lshlrev_b64 v[2:3], 10, v[0:1]
	s_waitcnt lgkmcnt(0)
	s_add_u32 s2, s58, s2
	v_lshl_add_u64 v[2:3], s[56:57], 0, v[2:3]
	v_lshlrev_b32_e32 v4, 6, v131
	s_addc_u32 s3, s59, 0
	v_bfe_u32 v6, v150, 5, 1
	v_lshl_add_u64 v[2:3], v[2:3], 0, s[10:11]
	v_ashrrev_i32_e32 v5, 31, v4
	s_add_u32 s2, s2, s10
	v_lshlrev_b64 v[132:133], 9, v[0:1]
	v_lshl_add_u64 v[2:3], v[4:5], 1, v[2:3]
	v_lshlrev_b32_e32 v0, 4, v6
	s_addc_u32 s3, s3, 0
	s_lshl_b32 s4, s4, 9
	v_lshl_add_u64 v[2:3], v[2:3], 0, v[0:1]
	s_or_b32 s4, s4, s31
	v_ashrrev_i32_e32 v134, 3, v150
	global_load_dwordx4 v[98:101], v[2:3], off
	global_load_dwordx4 v[102:105], v[2:3], off offset:32
	global_load_dwordx4 v[106:109], v[2:3], off offset:64
	global_load_dwordx4 v[110:113], v[2:3], off offset:96
	s_mulk_i32 s4, 0x2100
	v_lshlrev_b32_e32 v3, 1, v134
	v_lshrrev_b32_e32 v4, 1, v134
	s_add_u32 s4, s64, s4
	v_and_b32_e32 v2, 0xffffff3, v134
	v_and_b32_e32 v3, 8, v3
	v_and_b32_e32 v4, 4, v4
	v_ashrrev_i32_e32 v135, 31, v134
	s_addc_u32 s5, s65, 0
	v_or3_b32 v20, v3, v2, v4
	v_lshlrev_b64 v[2:3], 10, v[134:135]
	v_lshlrev_b32_e32 v4, 4, v150
	v_lshl_add_u64 v[2:3], s[2:3], 0, v[2:3]
	v_and_b32_e32 v136, 0x70, v4
	v_mov_b32_e32 v137, v1
	v_mov_b64_e32 v[14:15], s[4:5]
	s_movk_i32 s6, 0x2100
	v_lshlrev_b32_e32 v130, 3, v6
	v_lshl_add_u64 v[6:7], v[2:3], 0, v[136:137]
	v_mad_i64_i32 v[10:11], s[4:5], v134, s6, v[14:15]
	v_add_u32_e32 v18, 64, v134
	global_load_dwordx4 v[2:5], v[6:7], off
	s_nop 0
	global_load_dwordx4 v[6:9], v[6:7], off offset:128
	v_lshl_add_u64 v[138:139], v[10:11], 0, v[136:137]
	v_mad_i64_i32 v[14:15], s[4:5], v18, s6, v[14:15]
	global_load_dwordx4 v[10:13], v[138:139], off
	v_lshl_add_u64 v[140:141], v[14:15], 0, v[136:137]
	global_load_dwordx4 v[14:17], v[140:141], off
	v_mul_lo_u32 v135, v20, s78
	v_add_u32_e32 v20, v135, v136
	v_mul_lo_u32 v154, v134, s78
	v_ashrrev_i32_e32 v19, 31, v18
	v_mov_b32_e32 v50, v1
	v_mov_b32_e32 v51, v1
	s_lshl_b32 s10, s7, 1
	v_mov_b32_e32 v52, v1
	v_mov_b32_e32 v53, v1
	v_mov_b32_e32 v54, v1
	v_mov_b32_e32 v55, v1
	v_mov_b32_e32 v56, v1
	v_mov_b32_e32 v57, v1
	v_mov_b32_e32 v58, v1
	v_mov_b32_e32 v59, v1
	v_mov_b32_e32 v60, v1
	v_mov_b32_e32 v61, v1
	v_mov_b32_e32 v62, v1
	v_mov_b32_e32 v63, v1
	s_waitcnt vmcnt(19)
	v_mov_b32_e32 v64, v1
	v_mov_b32_e32 v65, v1
	s_waitcnt vmcnt(8)
	v_mov_b64_e32 v[34:35], v[50:51]
	v_and_b32_e32 v151, 63, v150
	s_add_i32 s42, s10, 2
	v_lshl_add_u64 v[142:143], s[2:3], 0, v[136:137]
	v_subrev_u32_e32 v156, 63, v152
	v_add_u32_e32 v157, 0xffffff90, v152
	v_or_b32_e32 v158, 31, v152
	v_mul_u32_u24_e32 v159, 0x90, v148
	v_mov_b32_e32 v161, 0xf149f2ca
	v_mov_b32_e32 v160, 0
	v_mov_b64_e32 v[36:37], v[52:53]
	v_mov_b64_e32 v[38:39], v[54:55]
	s_waitcnt vmcnt(3)
	ds_write_b128 v20, v[2:5]
	s_waitcnt vmcnt(2)
	ds_write_b128 v20, v[6:9] offset:9216
	v_add_u32_e32 v2, v154, v136
	s_waitcnt vmcnt(1)
	ds_write_b128 v2, v[10:13] offset:18432
	s_waitcnt vmcnt(0)
	ds_write_b128 v2, v[14:17] offset:27648
	v_lshlrev_b64 v[2:3], 10, v[18:19]
	v_lshl_add_u64 v[2:3], s[2:3], 0, v[2:3]
	v_lshl_add_u64 v[2:3], v[2:3], 0, v[136:137]
	global_load_dwordx4 v[114:117], v[2:3], off
	global_load_dwordx4 v[118:121], v[2:3], off offset:128
	global_load_dwordx4 v[122:125], v[138:139], off offset:128
	global_load_dwordx4 v[126:129], v[140:141], off offset:128
	v_add_u32_e32 v2, -4, v213
	v_mov_b32_e32 v3, 0xff800000
	ds_write_b32 v2, v3
	s_waitcnt lgkmcnt(0)
	s_barrier
	ds_read_b32 v155, v204
	v_mov_b64_e32 v[2:3], v[50:51]
	v_mov_b64_e32 v[18:19], v[50:51]
	v_mul_i32_i24_e32 v137, 0x2400, v131
	s_mov_b32 s2, 0
	v_mov_b64_e32 v[4:5], v[52:53]
	v_mov_b64_e32 v[6:7], v[54:55]
	v_mov_b64_e32 v[8:9], v[56:57]
	v_mov_b64_e32 v[10:11], v[58:59]
	v_mov_b64_e32 v[12:13], v[60:61]
	v_mov_b64_e32 v[14:15], v[62:63]
	v_mov_b64_e32 v[16:17], v[64:65]
	v_mov_b64_e32 v[20:21], v[52:53]
	v_mov_b64_e32 v[22:23], v[54:55]
	v_mov_b64_e32 v[24:25], v[56:57]
	v_mov_b64_e32 v[26:27], v[58:59]
	v_mov_b64_e32 v[28:29], v[60:61]
	v_mov_b64_e32 v[30:31], v[62:63]
	v_mov_b64_e32 v[32:33], v[64:65]
	v_mov_b64_e32 v[40:41], v[56:57]
	v_mov_b64_e32 v[42:43], v[58:59]
	v_mov_b64_e32 v[44:45], v[60:61]
	v_mov_b64_e32 v[46:47], v[62:63]
	v_mov_b64_e32 v[48:49], v[64:65]

; DI f32x16 mfma32(bf16x8 a, bf16x8 b, f32x16 c) { return __builtin_amdgcn_mfma_f32_32x32x16_bf16(a, b, c, 0, 0, 0); }
; DI void diff_map(const unsigned char* sk, const bf16x8 (&qf)[4], const unsigned char* sv, const float* lut, bool far,
;                  bool diag, int ks0, int tq, int h, int lq, f32x16 (&O)[4], float& m, float& l) {
;     ...
;   f32x16 S = zero16();
; #pragma unroll
;   for (int s = 0; s < 4; ++s) {
;     bf16x8 kf = *(const bf16x8*)(sk + lq * 144 + (16 * s + 8 * h) * 2);
;     S = mfma32(kf, qf[s], S);
;   }
;     ...
;   } else {
;     float mx = -1e30f;
; #pragma unroll
;     for (int i = 0; i < 16; ++i) {
;       const int key = ks0 + 16 * (i >> 3) + 8 * h + (i & 7);
;       int d = tq - key;
;       const bool msk = diag && d < 0;
;       d = d < 0 ? 0 : (d > 128 ? 128 : d);
;       float x = S[i] * csc + lut[d];
;       if (msk) x = -1e30f;
;       S[i] = x;
;       mx = fmaxf(mx, x);
;     }
;     mx = fmaxf(mx, __shfl_xor(mx, 32));
;     const float mn = fmaxf(m, mx);
;     if (__any(mn > m + 8.f)) {
;       const float a = __builtin_amdgcn_exp2f(m - mn);
;       l *= a; m = mn;
; #pragma unroll
;       for (int d = 0; d < 4; ++d) O[d] *= a;
;     }
.LBB0_928:
	s_lshl_b32 s4, s46, 5
	s_or_b32 s4, s4, s45
	v_cmp_le_u32_e32 vcc, s4, v158
	s_or_b64 s[8:9], s[8:9], exec
	s_and_saveexec_b64 s[34:35], vcc
	s_cbranch_execz .LBB0_927
	s_mul_i32 s5, s46, 0x1200
	v_add_u32_e32 v86, s5, v162
	ds_read_b128 v[66:69], v86
	ds_read_b128 v[82:85], v86 offset:32
	s_or_b32 s5, s4, 31
	v_cmp_ge_i32_e32 vcc, s5, v157
	v_add_f32_e32 v168, 0x41000000, v161
	s_waitcnt lgkmcnt(1)
	v_mfma_f32_32x32x16_bf16 v[66:81], v[66:69], v[98:101], 0
	s_waitcnt lgkmcnt(0)
	v_mfma_f32_32x32x16_bf16 v[66:81], v[82:85], v[102:105], v[66:81]
	ds_read_b128 v[82:85], v86 offset:64
	ds_read_b128 v[86:89], v86 offset:96
	s_waitcnt lgkmcnt(1)
	v_mfma_f32_32x32x16_bf16 v[66:81], v[82:85], v[106:109], v[66:81]
	s_waitcnt lgkmcnt(0)
	v_mfma_f32_32x32x16_bf16 v[66:81], v[86:89], v[110:113], v[66:81]
	s_and_saveexec_b64 s[28:29], vcc
	s_xor_b64 s[28:29], exec, s[28:29]
	s_cbranch_execz .LBB0_934
	v_or_b32_e32 v82, s4, v130
	v_sub_u32_e32 v82, v153, v82
	v_subrev_u32_e32 v83, 1, v82
	v_med3_i32 v83, v83, -1, v209
	v_lshl_add_u32 v83, v83, 2, v213
	ds_read_b32 v83, v83
	v_subrev_u32_e32 v84, 2, v82
	v_med3_i32 v84, v84, -1, v209
	v_lshl_add_u32 v84, v84, 2, v213
	ds_read_b32 v84, v84
	v_subrev_u32_e32 v85, 3, v82
	v_med3_i32 v85, v85, -1, v209
	v_lshl_add_u32 v85, v85, 2, v213
	ds_read_b32 v85, v85
	v_subrev_u32_e32 v86, 4, v82
	v_med3_i32 v86, v86, -1, v209
	v_lshl_add_u32 v86, v86, 2, v213
	ds_read_b32 v86, v86
	v_subrev_u32_e32 v87, 5, v82
	v_med3_i32 v87, v87, -1, v209
	v_lshl_add_u32 v87, v87, 2, v213
	ds_read_b32 v87, v87
	v_subrev_u32_e32 v88, 6, v82
	v_med3_i32 v88, v88, -1, v209
	v_lshl_add_u32 v88, v88, 2, v213
	ds_read_b32 v88, v88
	v_subrev_u32_e32 v89, 7, v82
	v_med3_i32 v89, v89, -1, v209
	v_lshl_add_u32 v89, v89, 2, v213
	ds_read_b32 v89, v89
	v_subrev_u32_e32 v90, 16, v82
	v_med3_i32 v90, v90, -1, v209
	v_lshl_add_u32 v90, v90, 2, v213
	ds_read_b32 v90, v90
	v_subrev_u32_e32 v91, 17, v82
	v_med3_i32 v91, v91, -1, v209
	v_lshl_add_u32 v91, v91, 2, v213
	ds_read_b32 v91, v91
	v_subrev_u32_e32 v92, 18, v82
	v_med3_i32 v92, v92, -1, v209
	v_lshl_add_u32 v92, v92, 2, v213
	ds_read_b32 v92, v92
	v_subrev_u32_e32 v93, 19, v82
	v_med3_i32 v93, v93, -1, v209
	v_lshl_add_u32 v93, v93, 2, v213
	ds_read_b32 v93, v93
	v_subrev_u32_e32 v94, 20, v82
	v_med3_i32 v94, v94, -1, v209
	v_lshl_add_u32 v94, v94, 2, v213
	ds_read_b32 v94, v94
	v_subrev_u32_e32 v95, 21, v82
	v_med3_i32 v95, v95, -1, v209
	v_lshl_add_u32 v95, v95, 2, v213
	ds_read_b32 v95, v95
	v_subrev_u32_e32 v96, 22, v82
	v_med3_i32 v96, v96, -1, v209
	v_lshl_add_u32 v96, v96, 2, v213
	ds_read_b32 v96, v96
	v_subrev_u32_e32 v97, 23, v82
	v_med3_i32 v97, v97, -1, v209
	v_lshl_add_u32 v97, v97, 2, v213
	ds_read_b32 v97, v97
	v_med3_i32 v82, v82, -1, v209
	v_lshl_add_u32 v82, v82, 2, v213
	ds_read_b32 v82, v82
	s_waitcnt lgkmcnt(0)
	v_fmamk_f32 v66, v66, 0x3e38aa3b, v82
	v_fmamk_f32 v67, v67, 0x3e38aa3b, v83
	v_fmamk_f32 v68, v68, 0x3e38aa3b, v84
	v_fmamk_f32 v69, v69, 0x3e38aa3b, v85
	v_fmamk_f32 v70, v70, 0x3e38aa3b, v86
	v_fmamk_f32 v71, v71, 0x3e38aa3b, v87
	v_fmamk_f32 v72, v72, 0x3e38aa3b, v88
	v_fmamk_f32 v73, v73, 0x3e38aa3b, v89
	v_fmamk_f32 v74, v74, 0x3e38aa3b, v90
	v_fmamk_f32 v75, v75, 0x3e38aa3b, v91
	v_fmamk_f32 v76, v76, 0x3e38aa3b, v92
	v_fmamk_f32 v77, v77, 0x3e38aa3b, v93
	v_fmamk_f32 v78, v78, 0x3e38aa3b, v94
	v_fmamk_f32 v79, v79, 0x3e38aa3b, v95
	v_fmamk_f32 v80, v80, 0x3e38aa3b, v96
	v_fmamk_f32 v81, v81, 0x3e38aa3b, v97
	v_max3_f32 v83, v66, s77, v67
	v_max3_f32 v83, v83, v68, v69
	v_max3_f32 v83, v83, v70, v71
	v_max3_f32 v83, v83, v72, v73
	v_max3_f32 v83, v83, v74, v75
	v_max3_f32 v83, v83, v76, v77
	v_max3_f32 v83, v83, v78, v79
	v_max3_f32 v82, v83, v80, v81
	v_and_b32_e32 v84, 64, v207
	v_add_u32_e32 v84, 64, v84
	v_xor_b32_e32 v83, 32, v207
	v_cmp_lt_i32_e32 vcc, v83, v84
	s_nop 1
	v_cndmask_b32_e32 v83, v207, v83, vcc
	v_lshlrev_b32_e32 v83, 2, v83
	ds_bpermute_b32 v83, v83, v82
	s_waitcnt lgkmcnt(0)
	v_max3_f32 v165, v161, v82, v83
	v_cmp_gt_f32_e32 vcc, v165, v168
	s_cbranch_vccz .LBB0_932
	v_sub_f32_e32 v82, v161, v165
	v_exp_f32_e32 v82, v82
	s_nop 0
	v_mul_f32_e32 v160, v160, v82
	v_pk_mul_f32 v[48:49], v[48:49], v[82:83] op_sel_hi:[1,0]
	v_pk_mul_f32 v[46:47], v[46:47], v[82:83] op_sel_hi:[1,0]
	v_pk_mul_f32 v[44:45], v[44:45], v[82:83] op_sel_hi:[1,0]
	v_pk_mul_f32 v[42:43], v[42:43], v[82:83] op_sel_hi:[1,0]
	v_pk_mul_f32 v[40:41], v[40:41], v[82:83] op_sel_hi:[1,0]
	v_pk_mul_f32 v[38:39], v[38:39], v[82:83] op_sel_hi:[1,0]
	v_pk_mul_f32 v[36:37], v[36:37], v[82:83] op_sel_hi:[1,0]
	v_pk_mul_f32 v[34:35], v[34:35], v[82:83] op_sel_hi:[1,0]
	v_pk_mul_f32 v[32:33], v[32:33], v[82:83] op_sel_hi:[1,0]
	v_pk_mul_f32 v[30:31], v[30:31], v[82:83] op_sel_hi:[1,0]
	v_pk_mul_f32 v[28:29], v[28:29], v[82:83] op_sel_hi:[1,0]
	v_pk_mul_f32 v[26:27], v[26:27], v[82:83] op_sel_hi:[1,0]
	v_pk_mul_f32 v[24:25], v[24:25], v[82:83] op_sel_hi:[1,0]
	v_pk_mul_f32 v[22:23], v[22:23], v[82:83] op_sel_hi:[1,0]
	v_pk_mul_f32 v[20:21], v[20:21], v[82:83] op_sel_hi:[1,0]
	v_pk_mul_f32 v[18:19], v[18:19], v[82:83] op_sel_hi:[1,0]
	v_pk_mul_f32 v[16:17], v[16:17], v[82:83] op_sel_hi:[1,0]
	v_pk_mul_f32 v[14:15], v[14:15], v[82:83] op_sel_hi:[1,0]
	v_pk_mul_f32 v[12:13], v[12:13], v[82:83] op_sel_hi:[1,0]
	v_pk_mul_f32 v[10:11], v[10:11], v[82:83] op_sel_hi:[1,0]
	v_pk_mul_f32 v[8:9], v[8:9], v[82:83] op_sel_hi:[1,0]
	v_pk_mul_f32 v[6:7], v[6:7], v[82:83] op_sel_hi:[1,0]
	v_pk_mul_f32 v[4:5], v[4:5], v[82:83] op_sel_hi:[1,0]
	v_pk_mul_f32 v[2:3], v[2:3], v[82:83] op_sel_hi:[1,0]
	v_pk_mul_f32 v[64:65], v[64:65], v[82:83] op_sel_hi:[1,0]
	v_pk_mul_f32 v[62:63], v[62:63], v[82:83] op_sel_hi:[1,0]
	v_pk_mul_f32 v[60:61], v[60:61], v[82:83] op_sel_hi:[1,0]
	v_pk_mul_f32 v[58:59], v[58:59], v[82:83] op_sel_hi:[1,0]
	v_pk_mul_f32 v[56:57], v[56:57], v[82:83] op_sel_hi:[1,0]
	v_pk_mul_f32 v[54:55], v[54:55], v[82:83] op_sel_hi:[1,0]
	v_pk_mul_f32 v[52:53], v[52:53], v[82:83] op_sel_hi:[1,0]
	v_pk_mul_f32 v[50:51], v[50:51], v[82:83] op_sel_hi:[1,0]
	s_branch .LBB0_933
